# grid barrier: non-leader workgroups poll the cross-XCC release generation directly (one relay hop fewer per barrier)
# speedup vs baseline: 1.0018x; 1.0018x over previous
.LBB0_115:
	s_or_b64 exec, exec, s[12:13]
	v_cvt_f32_u32_e32 v4, v2
	s_waitcnt vmcnt(0)
	v_readfirstlane_b32 s6, v3
	v_sub_u32_e32 v3, 0, v2
	v_rcp_iflag_f32_e32 v4, v4
	v_add_u32_e32 v5, s6, v1
	v_mul_f32_e32 v4, 0x4f7ffffe, v4
	v_cvt_u32_f32_e32 v4, v4
	v_mul_lo_u32 v1, v3, v4
	v_mul_hi_u32 v1, v4, v1
	v_add_u32_e32 v1, v4, v1
	v_mul_hi_u32 v1, v5, v1
	v_mul_lo_u32 v3, v1, v2
	v_sub_u32_e32 v3, v5, v3
	v_add_u32_e32 v4, 1, v1
	v_sub_u32_e32 v6, v3, v2
	v_cmp_ge_u32_e32 vcc, v3, v2
	s_nop 1
	v_cndmask_b32_e32 v1, v1, v4, vcc
	v_cndmask_b32_e32 v3, v3, v6, vcc
	v_add_u32_e32 v4, 1, v1
	v_cmp_ge_u32_e32 vcc, v3, v2
	v_add_u32_e32 v3, 1, v5
	s_nop 0
	v_cndmask_b32_e32 v1, v1, v4, vcc
	v_mul_lo_u32 v4, v2, v1
	v_add_u32_e32 v2, v4, v2
	v_cmp_ne_u32_e32 vcc, v3, v2
	s_and_saveexec_b64 s[6:7], vcc
	s_xor_b64 s[12:13], exec, s[6:7]
	s_cbranch_execz .LBB0_129
	v_readlane_b32 s6, v253, 22
	v_readlane_b32 s7, v253, 23
	s_waitcnt lgkmcnt(0)
	s_nop 3
	global_load_dword v0, v64, s[6:7] sc1
	s_waitcnt vmcnt(0)
	v_cmp_eq_u32_e32 vcc, v0, v1
	s_and_saveexec_b64 s[16:17], vcc
	s_cbranch_execz .LBB0_128
	s_mov_b32 s6, 1
	s_mov_b64 s[20:21], 0
	s_branch .LBB0_119

.LBB0_121:
	v_readlane_b32 s38, v253, 22
	v_readlane_b32 s39, v253, 23
	s_add_i32 s6, s6, 1
	s_mov_b64 s[40:41], -1
	s_nop 2
	global_load_dword v0, v64, s[38:39] sc1
	s_waitcnt vmcnt(0)
	v_cmp_ne_u32_e32 vcc, v0, v1
	s_orn2_b64 s[38:39], vcc, exec
	s_branch .LBB0_118

.LBB0_1155:
	s_or_b64 exec, exec, s[12:13]
	v_cvt_f32_u32_e32 v4, v2
	s_waitcnt vmcnt(0)
	v_readfirstlane_b32 s6, v3
	v_sub_u32_e32 v3, 0, v2
	v_rcp_iflag_f32_e32 v4, v4
	v_add_u32_e32 v5, s6, v1
	v_mul_f32_e32 v4, 0x4f7ffffe, v4
	v_cvt_u32_f32_e32 v4, v4
	v_mul_lo_u32 v1, v3, v4
	v_mul_hi_u32 v1, v4, v1
	v_add_u32_e32 v1, v4, v1
	v_mul_hi_u32 v1, v5, v1
	v_mul_lo_u32 v3, v1, v2
	v_sub_u32_e32 v3, v5, v3
	v_add_u32_e32 v4, 1, v1
	v_cmp_ge_u32_e32 vcc, v3, v2
	s_nop 1
	v_cndmask_b32_e32 v1, v1, v4, vcc
	v_sub_u32_e32 v4, v3, v2
	v_cndmask_b32_e32 v3, v3, v4, vcc
	v_add_u32_e32 v4, 1, v1
	v_cmp_ge_u32_e32 vcc, v3, v2
	v_add_u32_e32 v3, 1, v5
	s_nop 0
	v_cndmask_b32_e32 v1, v1, v4, vcc
	v_mul_lo_u32 v4, v2, v1
	v_add_u32_e32 v2, v4, v2
	v_cmp_ne_u32_e32 vcc, v3, v2
	s_and_saveexec_b64 s[6:7], vcc
	s_xor_b64 s[12:13], exec, s[6:7]
	s_cbranch_execz .LBB0_1169
	v_readlane_b32 s6, v253, 22
	v_readlane_b32 s7, v253, 23
	s_waitcnt lgkmcnt(0)
	s_nop 3
	global_load_dword v0, v64, s[6:7] sc1
	s_waitcnt vmcnt(0)
	v_cmp_eq_u32_e32 vcc, v0, v1
	s_and_saveexec_b64 s[16:17], vcc
	s_cbranch_execz .LBB0_1168
	s_mov_b32 s6, 1
	s_mov_b64 s[20:21], 0
	s_branch .LBB0_1159

.LBB0_1797:
	s_or_b64 exec, exec, s[12:13]
	v_cvt_f32_u32_e32 v4, v2
	s_waitcnt vmcnt(0)
	v_readfirstlane_b32 s2, v3
	v_sub_u32_e32 v3, 0, v2
	v_rcp_iflag_f32_e32 v4, v4
	v_add_u32_e32 v5, s2, v1
	v_mul_f32_e32 v4, 0x4f7ffffe, v4
	v_cvt_u32_f32_e32 v4, v4
	v_mul_lo_u32 v1, v3, v4
	v_mul_hi_u32 v1, v4, v1
	v_add_u32_e32 v1, v4, v1
	v_mul_hi_u32 v1, v5, v1
	v_mul_lo_u32 v3, v1, v2
	v_sub_u32_e32 v3, v5, v3
	v_add_u32_e32 v4, 1, v1
	v_cmp_ge_u32_e32 vcc, v3, v2
	s_nop 1
	v_cndmask_b32_e32 v1, v1, v4, vcc
	v_sub_u32_e32 v4, v3, v2
	v_cndmask_b32_e32 v3, v3, v4, vcc
	v_add_u32_e32 v4, 1, v1
	v_cmp_ge_u32_e32 vcc, v3, v2
	v_add_u32_e32 v3, 1, v5
	s_nop 0
	v_cndmask_b32_e32 v1, v1, v4, vcc
	v_mul_lo_u32 v4, v2, v1
	v_add_u32_e32 v2, v4, v2
	v_cmp_ne_u32_e32 vcc, v3, v2
	s_and_saveexec_b64 s[2:3], vcc
	s_xor_b64 s[12:13], exec, s[2:3]
	s_cbranch_execz .LBB0_1811
	v_readlane_b32 s2, v253, 22
	v_readlane_b32 s3, v253, 23
	s_waitcnt lgkmcnt(0)
	s_nop 3
	global_load_dword v0, v64, s[2:3] sc1
	s_waitcnt vmcnt(0)
	v_cmp_eq_u32_e32 vcc, v0, v1
	s_and_saveexec_b64 s[20:21], vcc
	s_cbranch_execz .LBB0_1810
	s_mov_b32 s2, 1
	s_mov_b64 s[28:29], 0
	s_branch .LBB0_1801

.LBB0_1803:
	v_readlane_b32 s6, v253, 22
	v_readlane_b32 s7, v253, 23
	s_add_i32 s2, s2, 1
	s_mov_b64 s[46:47], -1
	s_nop 2
	global_load_dword v0, v64, s[6:7] sc1
	s_waitcnt vmcnt(0)
	v_cmp_ne_u32_e32 vcc, v0, v1
	s_orn2_b64 s[44:45], vcc, exec
	s_branch .LBB0_1800

.LBB0_1924:
	s_or_b64 exec, exec, s[12:13]
	v_cvt_f32_u32_e32 v4, v2
	s_waitcnt vmcnt(0)
	v_readfirstlane_b32 s2, v3
	v_sub_u32_e32 v3, 0, v2
	v_rcp_iflag_f32_e32 v4, v4
	v_add_u32_e32 v5, s2, v1
	v_mul_f32_e32 v4, 0x4f7ffffe, v4
	v_cvt_u32_f32_e32 v4, v4
	v_mul_lo_u32 v1, v3, v4
	v_mul_hi_u32 v1, v4, v1
	v_add_u32_e32 v1, v4, v1
	v_mul_hi_u32 v1, v5, v1
	v_mul_lo_u32 v3, v1, v2
	v_sub_u32_e32 v3, v5, v3
	v_add_u32_e32 v4, 1, v1
	v_cmp_ge_u32_e32 vcc, v3, v2
	s_nop 1
	v_cndmask_b32_e32 v1, v1, v4, vcc
	v_sub_u32_e32 v4, v3, v2
	v_cndmask_b32_e32 v3, v3, v4, vcc
	v_add_u32_e32 v4, 1, v1
	v_cmp_ge_u32_e32 vcc, v3, v2
	v_add_u32_e32 v3, 1, v5
	s_nop 0
	v_cndmask_b32_e32 v1, v1, v4, vcc
	v_mul_lo_u32 v4, v2, v1
	v_add_u32_e32 v2, v4, v2
	v_cmp_ne_u32_e32 vcc, v3, v2
	s_and_saveexec_b64 s[2:3], vcc
	s_xor_b64 s[12:13], exec, s[2:3]
	s_cbranch_execz .LBB0_1938
	v_readlane_b32 s2, v253, 22
	v_readlane_b32 s3, v253, 23
	s_waitcnt lgkmcnt(0)
	s_nop 3
	global_load_dword v0, v64, s[2:3] sc1
	s_waitcnt vmcnt(0)
	v_cmp_eq_u32_e32 vcc, v0, v1
	s_and_saveexec_b64 s[20:21], vcc
	s_cbranch_execz .LBB0_1937
	s_mov_b32 s2, 1
	s_mov_b64 s[42:43], 0
	s_branch .LBB0_1928

.LBB0_1930:
	v_readlane_b32 s6, v253, 22
	v_readlane_b32 s7, v253, 23
	s_add_i32 s2, s2, 1
	s_mov_b64 s[48:49], -1
	s_nop 2
	global_load_dword v0, v64, s[6:7] sc1
	s_waitcnt vmcnt(0)
	v_cmp_ne_u32_e32 vcc, v0, v1
	s_orn2_b64 s[46:47], vcc, exec
	s_branch .LBB0_1927

.LBB0_2187:
	s_or_b64 exec, exec, s[12:13]
	v_cvt_f32_u32_e32 v4, v2
	s_waitcnt vmcnt(0)
	v_readfirstlane_b32 s2, v3
	v_sub_u32_e32 v3, 0, v2
	v_rcp_iflag_f32_e32 v4, v4
	v_add_u32_e32 v5, s2, v1
	v_mul_f32_e32 v4, 0x4f7ffffe, v4
	v_cvt_u32_f32_e32 v4, v4
	v_mul_lo_u32 v1, v3, v4
	v_mul_hi_u32 v1, v4, v1
	v_add_u32_e32 v1, v4, v1
	v_mul_hi_u32 v1, v5, v1
	v_mul_lo_u32 v3, v1, v2
	v_sub_u32_e32 v3, v5, v3
	v_add_u32_e32 v4, 1, v1
	v_cmp_ge_u32_e32 vcc, v3, v2
	s_nop 1
	v_cndmask_b32_e32 v1, v1, v4, vcc
	v_sub_u32_e32 v4, v3, v2
	v_cndmask_b32_e32 v3, v3, v4, vcc
	v_add_u32_e32 v4, 1, v1
	v_cmp_ge_u32_e32 vcc, v3, v2
	v_add_u32_e32 v3, 1, v5
	s_nop 0
	v_cndmask_b32_e32 v1, v1, v4, vcc
	v_mul_lo_u32 v4, v2, v1
	v_add_u32_e32 v2, v4, v2
	v_cmp_ne_u32_e32 vcc, v3, v2
	s_and_saveexec_b64 s[2:3], vcc
	s_xor_b64 s[12:13], exec, s[2:3]
	s_cbranch_execz .LBB0_2201
	v_readlane_b32 s2, v253, 22
	v_readlane_b32 s3, v253, 23
	s_waitcnt lgkmcnt(0)
	s_nop 3
	global_load_dword v0, v64, s[2:3] sc1
	s_waitcnt vmcnt(0)
	v_cmp_eq_u32_e32 vcc, v0, v1
	s_and_saveexec_b64 s[16:17], vcc
	s_cbranch_execz .LBB0_2200
	s_mov_b32 s2, 1
	s_mov_b64 s[20:21], 0
	s_branch .LBB0_2191

.LBB0_2193:
	v_readlane_b32 s38, v253, 22
	v_readlane_b32 s39, v253, 23
	s_add_i32 s2, s2, 1
	s_mov_b64 s[42:43], -1
	s_nop 2
	global_load_dword v0, v64, s[38:39] sc1
	s_waitcnt vmcnt(0)
	v_cmp_ne_u32_e32 vcc, v0, v1
	s_orn2_b64 s[40:41], vcc, exec
	s_branch .LBB0_2190

.LBB0_2261:
	s_or_b64 exec, exec, s[6:7]
	v_cvt_f32_u32_e32 v4, v2
	s_waitcnt vmcnt(0)
	v_readfirstlane_b32 s6, v3
	v_sub_u32_e32 v3, 0, v2
	v_rcp_iflag_f32_e32 v4, v4
	v_add_u32_e32 v5, s6, v1
	v_mul_f32_e32 v4, 0x4f7ffffe, v4
	v_cvt_u32_f32_e32 v4, v4
	v_mul_lo_u32 v1, v3, v4
	v_mul_hi_u32 v1, v4, v1
	v_add_u32_e32 v1, v4, v1
	v_mul_hi_u32 v1, v5, v1
	v_mul_lo_u32 v3, v1, v2
	v_sub_u32_e32 v3, v5, v3
	v_add_u32_e32 v4, 1, v1
	v_cmp_ge_u32_e32 vcc, v3, v2
	s_nop 1
	v_cndmask_b32_e32 v1, v1, v4, vcc
	v_sub_u32_e32 v4, v3, v2
	v_cndmask_b32_e32 v3, v3, v4, vcc
	v_add_u32_e32 v4, 1, v1
	v_cmp_ge_u32_e32 vcc, v3, v2
	v_add_u32_e32 v3, 1, v5
	s_nop 0
	v_cndmask_b32_e32 v1, v1, v4, vcc
	v_mul_lo_u32 v4, v2, v1
	v_add_u32_e32 v2, v4, v2
	v_cmp_ne_u32_e32 vcc, v3, v2
	s_and_saveexec_b64 s[6:7], vcc
	s_xor_b64 s[6:7], exec, s[6:7]
	s_cbranch_execz .LBB0_2275
	v_readlane_b32 s12, v253, 22
	v_readlane_b32 s13, v253, 23
	s_waitcnt lgkmcnt(0)
	s_nop 3
	global_load_dword v0, v64, s[12:13] sc1
	s_waitcnt vmcnt(0)
	v_cmp_eq_u32_e32 vcc, v0, v1
	s_and_saveexec_b64 s[12:13], vcc
	s_cbranch_execz .LBB0_2274
	s_mov_b32 s18, 1
	s_mov_b64 s[16:17], 0
	s_branch .LBB0_2265

.LBB0_2267:
	v_readlane_b32 s28, v253, 22
	v_readlane_b32 s29, v253, 23
	s_add_i32 s18, s18, 1
	s_mov_b64 s[38:39], -1
	s_nop 2
	global_load_dword v0, v64, s[28:29] sc1
	s_waitcnt vmcnt(0)
	v_cmp_ne_u32_e32 vcc, v0, v1
	s_orn2_b64 s[28:29], vcc, exec
	s_branch .LBB0_2264
